# P0's once-read loads: sc1 nt instead of nt
# speedup vs baseline: 1.0012x; 1.0012x over previous
; __device__ __forceinline__ void p0_prologue(const Args& a, LAS unsigned char* lds, int gw, int NGW, int wave, int lane) {
;     ...
;     for (int it = gw; it < NITEMS; it += NGW) {
;         int r = it;
;         if (r < 2 * I_GU) {
;             const bool second = r >= I_GU; if (second) r -= I_GU;
;             const int nblk = NGU / 32, kb = r / nblk, nb = r % nblk, n = nb * 32 + (lane & 31);
;             const float* wg = second ? a.w2g : a.w1g; const float* wu = second ? a.w2u : a.w1u;
;             const float* colp = (((n >> 7) & 1) ? wu : wg) + 128 * (n >> 8) + (n & 127);
;             transpose_item(colp, DFF, second ? a.g2 : a.g1, (bf16_t*)(ws + (second ? WS_W2GU : WS_W1GU)), DM, 0, kb * 64, nb * 32, scr, lane);
;             continue;
;         }
;         r -= 2 * I_GU;
;         if (r < 2 * I_D) {
;             const bool second = r >= I_D; if (second) r -= I_D;
;             const int nblk = DM / 32, kb = r / nblk, nb = r % nblk, n = nb * 32 + (lane & 31);
;             transpose_item((second ? a.w2d : a.w1d) + n, DM, nullptr, (bf16_t*)(ws + (second ? WS_W2D : WS_W1D)), DFF, 0, kb * 64, nb * 32, scr, lane);
;             continue;
;         }
;         r -= 2 * I_D;
;         if (r < I_IN) {
;             const int nblk = NIN / 32, kb = r / nblk, nb = r % nblk, n = nb * 32 + (lane & 31);
;             int src = -1;
;             if (n < 1536) src = n; else if (n < 2304) src = n + 8;
;             else if (n < 4352) { const int t = n - 2304; src = (((t >> 7) & 1) ? 3336 : 2312) + 128 * (t >> 8) + (t & 127); }
;             else if (n < 4360) src = n - 4352 + 1536;
;             transpose_item(src >= 0 ? a.win + src : nullptr, WIN_SRC, a.gmix, (bf16_t*)(ws + WS_WIN), DM, 0, kb * 64, nb * 32, scr, lane);
;             continue;
;         }
;         r -= I_IN;
;         if (r < 2 * I_BR) {
;             const bool second = r >= I_BR; if (second) r -= I_BR;
;             const int nblk = DM / 32, kb = r / nblk, nb = r % nblk, n = nb * 32 + (lane & 31);
;             transpose_item((second ? a.wba : a.wbm) + n, DM, nullptr, (bf16_t*)(ws + WS_WBR), DM, second ? 512 : 0, kb * 64, nb * 32, scr, lane);
;             continue;
;         }
;         r -= 2 * I_BR;
;         { const int nblk = DM / 32, kb = r / nblk, nb = r % nblk, n = nb * 32 + (lane & 31);
.LBB0_27:
	s_cmpk_gt_i32 s87, 0x15ff
	s_mov_b64 s[2:3], -1
	s_cbranch_scc0 .LBB0_330
	s_cmpk_gt_u32 s87, 0x20ff
	s_cbranch_scc0 .LBB0_263
	s_cmpk_gt_u32 s87, 0x29ff
	s_cbranch_scc0 .LBB0_162
	s_cmpk_gt_u32 s87, 0x2bff
	s_cbranch_scc0 .LBB0_96
	s_and_b32 s38, s33, 0x3e0
	v_or_b32_e32 v4, s38, v3
	s_and_b32 s2, s78, 0x7fffffc0
	v_lshlrev_b32_e32 v4, 2, v4
	s_add_i32 s6, s2, 0xffffa800
	v_lshl_add_u64 v[10:11], s[68:69], 0, v[4:5]
	v_or_b32_e32 v4, s6, v0
	v_mov_b32_e32 v12, 0
	v_cmp_ne_u32_e64 s[2:3], 1, v48
	s_andn2_b64 vcc, exec, s[30:31]
	v_mov_b32_e32 v13, 0
	s_cbranch_vccnz .LBB0_33
	v_lshlrev_b64 v[14:15], 12, v[4:5]
	v_lshl_add_u64 v[14:15], v[10:11], 0, v[14:15]
	global_load_dword v13, v[14:15], off sc1 nt
.LBB0_33:
	s_and_b64 vcc, exec, s[2:3]
	s_cbranch_vccnz .LBB0_35
	v_or_b32_e32 v14, 2, v4
	v_mov_b32_e32 v15, v5
	v_lshlrev_b64 v[14:15], 12, v[14:15]
	v_lshl_add_u64 v[14:15], v[10:11], 0, v[14:15]
	global_load_dword v12, v[14:15], off sc1 nt
.LBB0_35:
	v_mov_b32_e32 v14, 0
	s_and_b64 vcc, exec, s[2:3]
	v_mov_b32_e32 v15, 0
	s_cbranch_vccnz .LBB0_37
	v_or_b32_e32 v16, 4, v4
	v_mov_b32_e32 v17, v5
	v_lshlrev_b64 v[16:17], 12, v[16:17]
	v_lshl_add_u64 v[16:17], v[10:11], 0, v[16:17]
	global_load_dword v15, v[16:17], off sc1 nt
.LBB0_37:
	s_and_b64 vcc, exec, s[2:3]
	s_cbranch_vccnz .LBB0_39
	v_or_b32_e32 v16, 6, v4
	v_mov_b32_e32 v17, v5
	v_lshlrev_b64 v[16:17], 12, v[16:17]
	v_lshl_add_u64 v[16:17], v[10:11], 0, v[16:17]
	global_load_dword v14, v[16:17], off sc1 nt
.LBB0_39:
	v_mov_b32_e32 v16, 0
	s_and_b64 vcc, exec, s[2:3]
	v_mov_b32_e32 v17, 0
	s_cbranch_vccnz .LBB0_41
	v_or_b32_e32 v18, 8, v4
	v_mov_b32_e32 v19, v5
	v_lshlrev_b64 v[18:19], 12, v[18:19]
	v_lshl_add_u64 v[18:19], v[10:11], 0, v[18:19]
	global_load_dword v17, v[18:19], off sc1 nt
.LBB0_41:
	s_and_b64 vcc, exec, s[2:3]
	s_cbranch_vccnz .LBB0_43
	v_or_b32_e32 v18, 10, v4
	v_mov_b32_e32 v19, v5
	v_lshlrev_b64 v[18:19], 12, v[18:19]
	v_lshl_add_u64 v[18:19], v[10:11], 0, v[18:19]
	global_load_dword v16, v[18:19], off sc1 nt
.LBB0_43:
	v_mov_b32_e32 v18, 0
	s_and_b64 vcc, exec, s[2:3]
	v_mov_b32_e32 v19, 0
	s_cbranch_vccnz .LBB0_45
	v_or_b32_e32 v20, 12, v4
	v_mov_b32_e32 v21, v5
	v_lshlrev_b64 v[20:21], 12, v[20:21]
	v_lshl_add_u64 v[20:21], v[10:11], 0, v[20:21]
	global_load_dword v19, v[20:21], off sc1 nt
.LBB0_45:
	s_and_b64 vcc, exec, s[2:3]
	s_cbranch_vccnz .LBB0_47
	v_or_b32_e32 v20, 14, v4
	v_mov_b32_e32 v21, v5
	v_lshlrev_b64 v[20:21], 12, v[20:21]
	v_lshl_add_u64 v[20:21], v[10:11], 0, v[20:21]
	global_load_dword v18, v[20:21], off sc1 nt
.LBB0_47:
	v_mov_b32_e32 v20, 0
	s_and_b64 vcc, exec, s[2:3]
	v_mov_b32_e32 v21, 0
	s_cbranch_vccnz .LBB0_49
	v_or_b32_e32 v22, 16, v4
	v_mov_b32_e32 v23, v5
	v_lshlrev_b64 v[22:23], 12, v[22:23]
	v_lshl_add_u64 v[22:23], v[10:11], 0, v[22:23]
	global_load_dword v21, v[22:23], off sc1 nt
.LBB0_49:
	s_and_b64 vcc, exec, s[2:3]
	s_cbranch_vccnz .LBB0_51
	v_or_b32_e32 v22, 18, v4
	v_mov_b32_e32 v23, v5
	v_lshlrev_b64 v[22:23], 12, v[22:23]
	v_lshl_add_u64 v[22:23], v[10:11], 0, v[22:23]
	global_load_dword v20, v[22:23], off sc1 nt
.LBB0_51:
	v_mov_b32_e32 v22, 0
	s_and_b64 vcc, exec, s[2:3]
	v_mov_b32_e32 v23, 0
	s_cbranch_vccnz .LBB0_53
	v_or_b32_e32 v24, 20, v4
	v_mov_b32_e32 v25, v5
	v_lshlrev_b64 v[24:25], 12, v[24:25]
	v_lshl_add_u64 v[24:25], v[10:11], 0, v[24:25]
	global_load_dword v23, v[24:25], off sc1 nt
.LBB0_53:
	s_and_b64 vcc, exec, s[2:3]
	s_cbranch_vccnz .LBB0_55
	v_or_b32_e32 v24, 22, v4
	v_mov_b32_e32 v25, v5
	v_lshlrev_b64 v[24:25], 12, v[24:25]
	v_lshl_add_u64 v[24:25], v[10:11], 0, v[24:25]
	global_load_dword v22, v[24:25], off sc1 nt
.LBB0_55:
	v_mov_b32_e32 v24, 0
	s_and_b64 vcc, exec, s[2:3]
	v_mov_b32_e32 v25, 0
	s_cbranch_vccnz .LBB0_57
	v_or_b32_e32 v26, 24, v4
	v_mov_b32_e32 v27, v5
	v_lshlrev_b64 v[26:27], 12, v[26:27]
	v_lshl_add_u64 v[26:27], v[10:11], 0, v[26:27]
	global_load_dword v25, v[26:27], off sc1 nt
.LBB0_57:
	s_and_b64 vcc, exec, s[2:3]
	s_cbranch_vccnz .LBB0_59
	v_or_b32_e32 v26, 26, v4
	v_mov_b32_e32 v27, v5
	v_lshlrev_b64 v[26:27], 12, v[26:27]
	v_lshl_add_u64 v[26:27], v[10:11], 0, v[26:27]
	global_load_dword v24, v[26:27], off sc1 nt
.LBB0_59:
	v_mov_b32_e32 v26, 0
	s_and_b64 vcc, exec, s[2:3]
	v_mov_b32_e32 v27, 0
	s_cbranch_vccnz .LBB0_61
	v_or_b32_e32 v28, 28, v4
	v_mov_b32_e32 v29, v5
	v_lshlrev_b64 v[28:29], 12, v[28:29]
	v_lshl_add_u64 v[28:29], v[10:11], 0, v[28:29]
	global_load_dword v27, v[28:29], off sc1 nt
; #define LAS __attribute__((address_space(3)))
; __device__ __forceinline__ void transpose_item(const float* colp, int N, const float* gk, bf16_t* WT, int ldw, int koff, int k0, int n0, LAS float* scr, int lane) {
;     float v[32];
; #pragma unroll
;     for (int i = 0; i < 32; ++i) { const int kk = 2 * i + (lane >> 5); v[i] = colp ? colp[(size_t)(k0 + kk) * N] : 0.f; }
; __device__ __forceinline__ void p0_prologue(const Args& a, LAS unsigned char* lds, int gw, int NGW, int wave, int lane) {
;     ...
;         r -= 2 * I_BR;
;         { const int nblk = DM / 32, kb = r / nblk, nb = r % nblk, n = nb * 32 + (lane & 31);
;           transpose_item(a.wo + n, DM, nullptr, (bf16_t*)(ws + WS_WO), DM, 0, kb * 64, nb * 32, scr, lane); }
.LBB0_61:
	s_and_b64 vcc, exec, s[2:3]
	s_cbranch_vccnz .LBB0_63
	v_or_b32_e32 v28, 30, v4
	v_mov_b32_e32 v29, v5
	v_lshlrev_b64 v[28:29], 12, v[28:29]
	v_lshl_add_u64 v[28:29], v[10:11], 0, v[28:29]
	global_load_dword v26, v[28:29], off sc1 nt
.LBB0_63:
	v_mov_b32_e32 v28, 0
	s_and_b64 vcc, exec, s[2:3]
	v_mov_b32_e32 v29, 0
	s_cbranch_vccnz .LBB0_65
	v_or_b32_e32 v50, 32, v4
	v_mov_b32_e32 v51, v5
	v_lshlrev_b64 v[50:51], 12, v[50:51]
	v_lshl_add_u64 v[50:51], v[10:11], 0, v[50:51]
	global_load_dword v29, v[50:51], off sc1 nt
.LBB0_65:
	s_and_b64 vcc, exec, s[2:3]
	s_cbranch_vccnz .LBB0_67
	v_or_b32_e32 v50, 34, v4
	v_mov_b32_e32 v51, v5
	v_lshlrev_b64 v[50:51], 12, v[50:51]
	v_lshl_add_u64 v[50:51], v[10:11], 0, v[50:51]
	global_load_dword v28, v[50:51], off sc1 nt
.LBB0_67:
	v_mov_b32_e32 v49, 0
	s_and_b64 vcc, exec, s[2:3]
	v_mov_b32_e32 v50, 0
	s_cbranch_vccnz .LBB0_69
	v_or_b32_e32 v50, 36, v4
	v_mov_b32_e32 v51, v5
	v_lshlrev_b64 v[50:51], 12, v[50:51]
	v_lshl_add_u64 v[50:51], v[10:11], 0, v[50:51]
	global_load_dword v50, v[50:51], off sc1 nt
.LBB0_69:
	s_and_b64 vcc, exec, s[2:3]
	s_cbranch_vccnz .LBB0_71
	v_or_b32_e32 v52, 38, v4
	v_mov_b32_e32 v53, v5
	v_lshlrev_b64 v[52:53], 12, v[52:53]
	v_lshl_add_u64 v[52:53], v[10:11], 0, v[52:53]
	global_load_dword v49, v[52:53], off sc1 nt
.LBB0_71:
	v_mov_b32_e32 v51, 0
	s_and_b64 vcc, exec, s[2:3]
	v_mov_b32_e32 v52, 0
	s_cbranch_vccnz .LBB0_73
	v_or_b32_e32 v52, 40, v4
	v_mov_b32_e32 v53, v5
	v_lshlrev_b64 v[52:53], 12, v[52:53]
	v_lshl_add_u64 v[52:53], v[10:11], 0, v[52:53]
	global_load_dword v52, v[52:53], off sc1 nt
.LBB0_73:
	s_and_b64 vcc, exec, s[2:3]
	s_cbranch_vccnz .LBB0_75
	v_or_b32_e32 v54, 42, v4
	v_mov_b32_e32 v55, v5
	v_lshlrev_b64 v[54:55], 12, v[54:55]
	v_lshl_add_u64 v[54:55], v[10:11], 0, v[54:55]
	global_load_dword v51, v[54:55], off sc1 nt
.LBB0_75:
	v_mov_b32_e32 v53, 0
	s_and_b64 vcc, exec, s[2:3]
	v_mov_b32_e32 v54, 0
	s_cbranch_vccnz .LBB0_77
	v_or_b32_e32 v54, 44, v4
	v_mov_b32_e32 v55, v5
	v_lshlrev_b64 v[54:55], 12, v[54:55]
	v_lshl_add_u64 v[54:55], v[10:11], 0, v[54:55]
	global_load_dword v54, v[54:55], off sc1 nt
.LBB0_77:
	s_and_b64 vcc, exec, s[2:3]
	s_cbranch_vccnz .LBB0_79
	v_or_b32_e32 v56, 46, v4
	v_mov_b32_e32 v57, v5
	v_lshlrev_b64 v[56:57], 12, v[56:57]
	v_lshl_add_u64 v[56:57], v[10:11], 0, v[56:57]
	global_load_dword v53, v[56:57], off sc1 nt
.LBB0_79:
	v_mov_b32_e32 v55, 0
	s_and_b64 vcc, exec, s[2:3]
	v_mov_b32_e32 v56, 0
	s_cbranch_vccnz .LBB0_81
	v_or_b32_e32 v56, 48, v4
	v_mov_b32_e32 v57, v5
	v_lshlrev_b64 v[56:57], 12, v[56:57]
	v_lshl_add_u64 v[56:57], v[10:11], 0, v[56:57]
	global_load_dword v56, v[56:57], off sc1 nt
.LBB0_81:
	s_and_b64 vcc, exec, s[2:3]
	s_cbranch_vccnz .LBB0_83
	v_or_b32_e32 v58, 50, v4
	v_mov_b32_e32 v59, v5
	v_lshlrev_b64 v[58:59], 12, v[58:59]
	v_lshl_add_u64 v[58:59], v[10:11], 0, v[58:59]
	global_load_dword v55, v[58:59], off sc1 nt
.LBB0_83:
	v_mov_b32_e32 v57, 0
	s_and_b64 vcc, exec, s[2:3]
	v_mov_b32_e32 v58, 0
	s_cbranch_vccnz .LBB0_85
	v_or_b32_e32 v58, 52, v4
	v_mov_b32_e32 v59, v5
	v_lshlrev_b64 v[58:59], 12, v[58:59]
	v_lshl_add_u64 v[58:59], v[10:11], 0, v[58:59]
	global_load_dword v58, v[58:59], off sc1 nt
.LBB0_85:
	s_and_b64 vcc, exec, s[2:3]
	s_cbranch_vccnz .LBB0_87
	v_or_b32_e32 v60, 54, v4
	v_mov_b32_e32 v61, v5
	v_lshlrev_b64 v[60:61], 12, v[60:61]
	v_lshl_add_u64 v[60:61], v[10:11], 0, v[60:61]
	global_load_dword v57, v[60:61], off sc1 nt
.LBB0_87:
	v_mov_b32_e32 v59, 0
	s_and_b64 vcc, exec, s[2:3]
	v_mov_b32_e32 v60, 0
	s_cbranch_vccnz .LBB0_89
	v_or_b32_e32 v60, 56, v4
	v_mov_b32_e32 v61, v5
	v_lshlrev_b64 v[60:61], 12, v[60:61]
	v_lshl_add_u64 v[60:61], v[10:11], 0, v[60:61]
	global_load_dword v60, v[60:61], off sc1 nt
.LBB0_89:
	s_and_b64 vcc, exec, s[2:3]
	s_cbranch_vccnz .LBB0_91
	v_or_b32_e32 v62, 58, v4
	v_mov_b32_e32 v63, v5
	v_lshlrev_b64 v[62:63], 12, v[62:63]
	v_lshl_add_u64 v[62:63], v[10:11], 0, v[62:63]
	global_load_dword v59, v[62:63], off sc1 nt
.LBB0_91:
	v_mov_b32_e32 v61, 0
	s_and_b64 vcc, exec, s[2:3]
	v_mov_b32_e32 v62, 0
	s_cbranch_vccnz .LBB0_93
	v_or_b32_e32 v62, 60, v4
	v_mov_b32_e32 v63, v5
	v_lshlrev_b64 v[62:63], 12, v[62:63]
	v_lshl_add_u64 v[62:63], v[10:11], 0, v[62:63]
	global_load_dword v62, v[62:63], off sc1 nt
.LBB0_93:
	s_and_b64 vcc, exec, s[2:3]
	s_cbranch_vccnz .LBB0_95
	v_or_b32_e32 v4, 62, v4
	v_lshlrev_b64 v[64:65], 12, v[4:5]
	v_lshl_add_u64 v[10:11], v[10:11], 0, v[64:65]
	global_load_dword v61, v[10:11], off sc1 nt

; #define LAS __attribute__((address_space(3)))
; __device__ __forceinline__ void transpose_item(const float* colp, int N, const float* gk, bf16_t* WT, int ldw, int koff, int k0, int n0, LAS float* scr, int lane) {
;     float v[32];
; #pragma unroll
;     for (int i = 0; i < 32; ++i) { const int kk = 2 * i + (lane >> 5); v[i] = colp ? colp[(size_t)(k0 + kk) * N] : 0.f; }
; __device__ __forceinline__ void p0_prologue(const Args& a, LAS unsigned char* lds, int gw, int NGW, int wave, int lane) {
;     ...
;         r -= I_IN;
;         if (r < 2 * I_BR) {
;             const bool second = r >= I_BR; if (second) r -= I_BR;
;             const int nblk = DM / 32, kb = r / nblk, nb = r % nblk, n = nb * 32 + (lane & 31);
;             transpose_item((second ? a.wba : a.wbm) + n, DM, nullptr, (bf16_t*)(ws + WS_WBR), DM, second ? 512 : 0, kb * 64, nb * 32, scr, lane);
;             continue;
.LBB0_96:
	s_and_b64 vcc, exec, s[2:3]
	s_cbranch_vccz .LBB0_427
	s_cmpk_gt_u32 s87, 0x2aff
	s_cselect_b64 s[38:39], -1, 0
	s_and_b64 s[2:3], s[38:39], exec
	s_cselect_b32 s2, s80, 0xffffd600
	s_add_i32 s40, s2, s87
	s_lshl_b32 s2, s40, 5
	s_and_b32 s6, s2, 0x3e0
	s_and_b64 s[2:3], s[38:39], exec
	s_cselect_b32 s3, s67, s65
	s_cselect_b32 s2, s66, s64
	s_lshl_b32 s40, s40, 1
	v_or_b32_e32 v4, s6, v3
	s_and_b32 s42, s40, 0x7fffffc0
	v_lshlrev_b32_e32 v4, 2, v4
	s_cmp_lg_u64 s[2:3], 0
	v_lshl_add_u64 v[10:11], s[2:3], 0, v[4:5]
	s_cselect_b64 s[40:41], -1, 0
	s_cmp_eq_u64 s[2:3], 0
	v_or_b32_e32 v4, s42, v0
	v_mov_b32_e32 v13, 0
	v_mov_b32_e32 v12, 0
	s_cbranch_scc1 .LBB0_99
	v_lshlrev_b64 v[14:15], 12, v[4:5]
	v_lshl_add_u64 v[14:15], v[10:11], 0, v[14:15]
	global_load_dword v12, v[14:15], off sc1 nt
.LBB0_99:
	v_cndmask_b32_e64 v14, 0, 1, s[40:41]
	v_cmp_ne_u32_e64 s[2:3], 1, v14
	s_andn2_b64 vcc, exec, s[40:41]
	s_cbranch_vccnz .LBB0_101
	v_or_b32_e32 v14, 2, v4
	v_mov_b32_e32 v15, v5
	v_lshlrev_b64 v[14:15], 12, v[14:15]
	v_lshl_add_u64 v[14:15], v[10:11], 0, v[14:15]
	global_load_dword v13, v[14:15], off sc1 nt

; #define LAS __attribute__((address_space(3)))
; __device__ __forceinline__ void transpose_item(const float* colp, int N, const float* gk, bf16_t* WT, int ldw, int koff, int k0, int n0, LAS float* scr, int lane) {
;     float v[32];
; #pragma unroll
;     for (int i = 0; i < 32; ++i) { const int kk = 2 * i + (lane >> 5); v[i] = colp ? colp[(size_t)(k0 + kk) * N] : 0.f; }
; __device__ __forceinline__ void p0_prologue(const Args& a, LAS unsigned char* lds, int gw, int NGW, int wave, int lane) {
;     ...
;         r -= 2 * I_D;
;         if (r < I_IN) {
;             const int nblk = NIN / 32, kb = r / nblk, nb = r % nblk, n = nb * 32 + (lane & 31);
;             int src = -1;
;             if (n < 1536) src = n; else if (n < 2304) src = n + 8;
;             else if (n < 4352) { const int t = n - 2304; src = (((t >> 7) & 1) ? 3336 : 2312) + 128 * (t >> 8) + (t & 127); }
;             else if (n < 4360) src = n - 4352 + 1536;
;             transpose_item(src >= 0 ? a.win + src : nullptr, WIN_SRC, a.gmix, (bf16_t*)(ws + WS_WIN), DM, 0, kb * 64, nb * 32, scr, lane);
.LBB0_173:
	s_lshl_b32 s2, s6, 6
	s_and_b32 s6, s2, 0x7fc0
	v_or_b32_e32 v51, s6, v0
	v_cmp_lt_i32_e32 vcc, -1, v4
	v_lshl_add_u64 v[12:13], v[4:5], 2, s[22:23]
	v_mul_u32_u24_e32 v4, 0x1108, v51
	s_and_b64 s[2:3], vcc, s[36:37]
	v_mov_b32_e32 v29, 0
	v_lshlrev_b32_e32 v4, 2, v4
	v_mov_b32_e32 v28, 0
	s_and_saveexec_b64 s[38:39], s[2:3]
	s_cbranch_execz .LBB0_175
	v_lshl_add_u64 v[10:11], v[12:13], 0, v[4:5]
	global_load_dword v28, v[10:11], off sc1 nt
.LBB0_175:
	s_or_b64 exec, exec, s[38:39]
	s_and_saveexec_b64 s[38:39], s[2:3]
	s_cbranch_execz .LBB0_177
	v_lshl_add_u64 v[10:11], v[12:13], 0, v[4:5]
	v_add_co_u32_e32 v10, vcc, 0x8000, v10
	s_nop 1
	v_addc_co_u32_e32 v11, vcc, 0, v11, vcc
	global_load_dword v29, v[10:11], off offset:2112 sc1 nt
.LBB0_177:
	s_or_b64 exec, exec, s[38:39]
	v_mov_b32_e32 v10, 0
	v_mov_b32_e32 v11, 0
	s_and_saveexec_b64 s[38:39], s[2:3]
	s_cbranch_execz .LBB0_179
	v_lshl_add_u64 v[14:15], v[12:13], 0, v[4:5]
	v_add_co_u32_e32 v14, vcc, 0x11000, v14
	s_nop 1
	v_addc_co_u32_e32 v15, vcc, 0, v15, vcc
	global_load_dword v11, v[14:15], off offset:128 sc1 nt
.LBB0_179:
	s_or_b64 exec, exec, s[38:39]
	s_and_saveexec_b64 s[38:39], s[2:3]
	s_cbranch_execz .LBB0_181
	v_lshl_add_u64 v[14:15], v[12:13], 0, v[4:5]
	v_add_co_u32_e32 v14, vcc, 0x19000, v14
	s_nop 1
	v_addc_co_u32_e32 v15, vcc, 0, v15, vcc
	global_load_dword v10, v[14:15], off offset:2240 sc1 nt
.LBB0_181:
	s_or_b64 exec, exec, s[38:39]
	v_mov_b32_e32 v49, 0
	v_mov_b32_e32 v50, 0
	s_and_saveexec_b64 s[38:39], s[2:3]
	s_cbranch_execz .LBB0_183
	v_lshl_add_u64 v[14:15], v[12:13], 0, v[4:5]
	v_add_co_u32_e32 v14, vcc, 0x22000, v14
	s_nop 1
	v_addc_co_u32_e32 v15, vcc, 0, v15, vcc
	global_load_dword v50, v[14:15], off offset:256 sc1 nt
.LBB0_183:
	s_or_b64 exec, exec, s[38:39]
	s_and_saveexec_b64 s[38:39], s[2:3]
	s_cbranch_execz .LBB0_185
	v_lshl_add_u64 v[14:15], v[12:13], 0, v[4:5]
	v_add_co_u32_e32 v14, vcc, 0x2a000, v14
	s_nop 1
	v_addc_co_u32_e32 v15, vcc, 0, v15, vcc
	global_load_dword v49, v[14:15], off offset:2368 sc1 nt
.LBB0_185:
	s_or_b64 exec, exec, s[38:39]
	v_mov_b32_e32 v14, 0
	v_mov_b32_e32 v15, 0
	s_and_saveexec_b64 s[38:39], s[2:3]
	s_cbranch_execz .LBB0_187
	v_lshl_add_u64 v[16:17], v[12:13], 0, v[4:5]
	v_add_co_u32_e32 v16, vcc, 0x33000, v16
	s_nop 1
	v_addc_co_u32_e32 v17, vcc, 0, v17, vcc
	global_load_dword v15, v[16:17], off offset:384 sc1 nt
.LBB0_187:
	s_or_b64 exec, exec, s[38:39]
	s_and_saveexec_b64 s[38:39], s[2:3]
	s_cbranch_execz .LBB0_189
	v_lshl_add_u64 v[16:17], v[12:13], 0, v[4:5]
	v_add_co_u32_e32 v16, vcc, 0x3b000, v16
	s_nop 1
	v_addc_co_u32_e32 v17, vcc, 0, v17, vcc
	global_load_dword v14, v[16:17], off offset:2496 sc1 nt
.LBB0_189:
	s_or_b64 exec, exec, s[38:39]
	v_mov_b32_e32 v52, 0
	v_mov_b32_e32 v53, 0
	s_and_saveexec_b64 s[38:39], s[2:3]
	s_cbranch_execz .LBB0_191
	v_lshl_add_u64 v[16:17], v[12:13], 0, v[4:5]
	v_add_co_u32_e32 v16, vcc, 0x44000, v16
	s_nop 1
	v_addc_co_u32_e32 v17, vcc, 0, v17, vcc
	global_load_dword v53, v[16:17], off offset:512 sc1 nt
.LBB0_191:
	s_or_b64 exec, exec, s[38:39]
	s_and_saveexec_b64 s[38:39], s[2:3]
	s_cbranch_execz .LBB0_193
	v_lshl_add_u64 v[16:17], v[12:13], 0, v[4:5]
	v_add_co_u32_e32 v16, vcc, 0x4c000, v16
	s_nop 1
	v_addc_co_u32_e32 v17, vcc, 0, v17, vcc
	global_load_dword v52, v[16:17], off offset:2624 sc1 nt
.LBB0_193:
	s_or_b64 exec, exec, s[38:39]
	v_mov_b32_e32 v16, 0
	v_mov_b32_e32 v17, 0
	s_and_saveexec_b64 s[38:39], s[2:3]
	s_cbranch_execz .LBB0_195
	v_lshl_add_u64 v[18:19], v[12:13], 0, v[4:5]
	v_add_co_u32_e32 v18, vcc, 0x55000, v18
	s_nop 1
	v_addc_co_u32_e32 v19, vcc, 0, v19, vcc
	global_load_dword v17, v[18:19], off offset:640 sc1 nt
.LBB0_195:
	s_or_b64 exec, exec, s[38:39]
	s_and_saveexec_b64 s[38:39], s[2:3]
	s_cbranch_execz .LBB0_197
	v_lshl_add_u64 v[18:19], v[12:13], 0, v[4:5]
	v_add_co_u32_e32 v18, vcc, 0x5d000, v18
	s_nop 1
	v_addc_co_u32_e32 v19, vcc, 0, v19, vcc
	global_load_dword v16, v[18:19], off offset:2752 sc1 nt
.LBB0_197:
	s_or_b64 exec, exec, s[38:39]
	v_mov_b32_e32 v54, 0
	v_mov_b32_e32 v55, 0
	s_and_saveexec_b64 s[38:39], s[2:3]
	s_cbranch_execz .LBB0_199
	v_lshl_add_u64 v[18:19], v[12:13], 0, v[4:5]
	v_add_co_u32_e32 v18, vcc, 0x66000, v18
	s_nop 1
	v_addc_co_u32_e32 v19, vcc, 0, v19, vcc
	global_load_dword v55, v[18:19], off offset:768 sc1 nt
.LBB0_199:
	s_or_b64 exec, exec, s[38:39]
	s_and_saveexec_b64 s[38:39], s[2:3]
	s_cbranch_execz .LBB0_201
	v_lshl_add_u64 v[18:19], v[12:13], 0, v[4:5]
	v_add_co_u32_e32 v18, vcc, 0x6e000, v18
	s_nop 1
	v_addc_co_u32_e32 v19, vcc, 0, v19, vcc
	global_load_dword v54, v[18:19], off offset:2880 sc1 nt
.LBB0_201:
	s_or_b64 exec, exec, s[38:39]
	v_mov_b32_e32 v18, 0
	v_mov_b32_e32 v19, 0
	s_and_saveexec_b64 s[38:39], s[2:3]
	s_cbranch_execz .LBB0_203
	v_lshl_add_u64 v[20:21], v[12:13], 0, v[4:5]
	v_add_co_u32_e32 v20, vcc, 0x77000, v20
	s_nop 1
	v_addc_co_u32_e32 v21, vcc, 0, v21, vcc
	global_load_dword v19, v[20:21], off offset:896 sc1 nt
.LBB0_203:
	s_or_b64 exec, exec, s[38:39]
	s_and_saveexec_b64 s[38:39], s[2:3]
	s_cbranch_execz .LBB0_205
	v_lshl_add_u64 v[20:21], v[12:13], 0, v[4:5]
	v_add_co_u32_e32 v20, vcc, 0x7f000, v20
	s_nop 1
	v_addc_co_u32_e32 v21, vcc, 0, v21, vcc
	global_load_dword v18, v[20:21], off offset:3008 sc1 nt
; #define LAS __attribute__((address_space(3)))
; __device__ __forceinline__ void transpose_item(const float* colp, int N, const float* gk, bf16_t* WT, int ldw, int koff, int k0, int n0, LAS float* scr, int lane) {
;     float v[32];
; #pragma unroll
;     for (int i = 0; i < 32; ++i) { const int kk = 2 * i + (lane >> 5); v[i] = colp ? colp[(size_t)(k0 + kk) * N] : 0.f; }
; __device__ __forceinline__ void p0_prologue(const Args& a, LAS unsigned char* lds, int gw, int NGW, int wave, int lane) {
;     ...
;         r -= 2 * I_D;
;         if (r < I_IN) {
;             const int nblk = NIN / 32, kb = r / nblk, nb = r % nblk, n = nb * 32 + (lane & 31);
;             int src = -1;
;             if (n < 1536) src = n; else if (n < 2304) src = n + 8;
;             else if (n < 4352) { const int t = n - 2304; src = (((t >> 7) & 1) ? 3336 : 2312) + 128 * (t >> 8) + (t & 127); }
;             else if (n < 4360) src = n - 4352 + 1536;
;             transpose_item(src >= 0 ? a.win + src : nullptr, WIN_SRC, a.gmix, (bf16_t*)(ws + WS_WIN), DM, 0, kb * 64, nb * 32, scr, lane);
.LBB0_205:
	s_or_b64 exec, exec, s[38:39]
	v_mov_b32_e32 v56, 0
	v_mov_b32_e32 v57, 0
	s_and_saveexec_b64 s[38:39], s[2:3]
	s_cbranch_execz .LBB0_207
	v_lshl_add_u64 v[20:21], v[12:13], 0, v[4:5]
	v_add_co_u32_e32 v20, vcc, 0x88000, v20
	s_nop 1
	v_addc_co_u32_e32 v21, vcc, 0, v21, vcc
	global_load_dword v57, v[20:21], off offset:1024 sc1 nt
.LBB0_207:
	s_or_b64 exec, exec, s[38:39]
	s_and_saveexec_b64 s[38:39], s[2:3]
	s_cbranch_execz .LBB0_209
	v_lshl_add_u64 v[20:21], v[12:13], 0, v[4:5]
	v_add_co_u32_e32 v20, vcc, 0x90000, v20
	s_nop 1
	v_addc_co_u32_e32 v21, vcc, 0, v21, vcc
	global_load_dword v56, v[20:21], off offset:3136 sc1 nt
.LBB0_209:
	s_or_b64 exec, exec, s[38:39]
	v_mov_b32_e32 v20, 0
	v_mov_b32_e32 v21, 0
	s_and_saveexec_b64 s[38:39], s[2:3]
	s_cbranch_execz .LBB0_211
	v_lshl_add_u64 v[22:23], v[12:13], 0, v[4:5]
	v_add_co_u32_e32 v22, vcc, 0x99000, v22
	s_nop 1
	v_addc_co_u32_e32 v23, vcc, 0, v23, vcc
	global_load_dword v21, v[22:23], off offset:1152 sc1 nt
.LBB0_211:
	s_or_b64 exec, exec, s[38:39]
	s_and_saveexec_b64 s[38:39], s[2:3]
	s_cbranch_execz .LBB0_213
	v_lshl_add_u64 v[22:23], v[12:13], 0, v[4:5]
	v_add_co_u32_e32 v22, vcc, 0xa1000, v22
	s_nop 1
	v_addc_co_u32_e32 v23, vcc, 0, v23, vcc
	global_load_dword v20, v[22:23], off offset:3264 sc1 nt
.LBB0_213:
	s_or_b64 exec, exec, s[38:39]
	v_mov_b32_e32 v58, 0
	v_mov_b32_e32 v59, 0
	s_and_saveexec_b64 s[38:39], s[2:3]
	s_cbranch_execz .LBB0_215
	v_lshl_add_u64 v[22:23], v[12:13], 0, v[4:5]
	v_add_co_u32_e32 v22, vcc, 0xaa000, v22
	s_nop 1
	v_addc_co_u32_e32 v23, vcc, 0, v23, vcc
	global_load_dword v59, v[22:23], off offset:1280 sc1 nt
.LBB0_215:
	s_or_b64 exec, exec, s[38:39]
	s_and_saveexec_b64 s[38:39], s[2:3]
	s_cbranch_execz .LBB0_217
	v_lshl_add_u64 v[22:23], v[12:13], 0, v[4:5]
	v_add_co_u32_e32 v22, vcc, 0xb2000, v22
	s_nop 1
	v_addc_co_u32_e32 v23, vcc, 0, v23, vcc
	global_load_dword v58, v[22:23], off offset:3392 sc1 nt
.LBB0_217:
	s_or_b64 exec, exec, s[38:39]
	v_mov_b32_e32 v22, 0
	v_mov_b32_e32 v23, 0
	s_and_saveexec_b64 s[38:39], s[2:3]
	s_cbranch_execz .LBB0_219
	v_lshl_add_u64 v[24:25], v[12:13], 0, v[4:5]
	v_add_co_u32_e32 v24, vcc, 0xbb000, v24
	s_nop 1
	v_addc_co_u32_e32 v25, vcc, 0, v25, vcc
	global_load_dword v23, v[24:25], off offset:1408 sc1 nt
.LBB0_219:
	s_or_b64 exec, exec, s[38:39]
	s_and_saveexec_b64 s[38:39], s[2:3]
	s_cbranch_execz .LBB0_221
	v_lshl_add_u64 v[24:25], v[12:13], 0, v[4:5]
	v_add_co_u32_e32 v24, vcc, 0xc3000, v24
	s_nop 1
	v_addc_co_u32_e32 v25, vcc, 0, v25, vcc
	global_load_dword v22, v[24:25], off offset:3520 sc1 nt
.LBB0_221:
	s_or_b64 exec, exec, s[38:39]
	v_mov_b32_e32 v60, 0
	v_mov_b32_e32 v61, 0
	s_and_saveexec_b64 s[38:39], s[2:3]
	s_cbranch_execz .LBB0_223
	v_lshl_add_u64 v[24:25], v[12:13], 0, v[4:5]
	v_add_co_u32_e32 v24, vcc, 0xcc000, v24
	s_nop 1
	v_addc_co_u32_e32 v25, vcc, 0, v25, vcc
	global_load_dword v61, v[24:25], off offset:1536 sc1 nt
.LBB0_223:
	s_or_b64 exec, exec, s[38:39]
	s_and_saveexec_b64 s[38:39], s[2:3]
	s_cbranch_execz .LBB0_225
	v_lshl_add_u64 v[24:25], v[12:13], 0, v[4:5]
	v_add_co_u32_e32 v24, vcc, 0xd4000, v24
	s_nop 1
	v_addc_co_u32_e32 v25, vcc, 0, v25, vcc
	global_load_dword v60, v[24:25], off offset:3648 sc1 nt
.LBB0_225:
	s_or_b64 exec, exec, s[38:39]
	v_mov_b32_e32 v24, 0
	v_mov_b32_e32 v25, 0
	s_and_saveexec_b64 s[38:39], s[2:3]
	s_cbranch_execz .LBB0_227
	v_lshl_add_u64 v[26:27], v[12:13], 0, v[4:5]
	v_add_co_u32_e32 v26, vcc, 0xdd000, v26
	s_nop 1
	v_addc_co_u32_e32 v27, vcc, 0, v27, vcc
	global_load_dword v25, v[26:27], off offset:1664 sc1 nt
.LBB0_227:
	s_or_b64 exec, exec, s[38:39]
	s_and_saveexec_b64 s[38:39], s[2:3]
	s_cbranch_execz .LBB0_229
	v_lshl_add_u64 v[26:27], v[12:13], 0, v[4:5]
	v_add_co_u32_e32 v26, vcc, 0xe5000, v26
	s_nop 1
	v_addc_co_u32_e32 v27, vcc, 0, v27, vcc
	global_load_dword v24, v[26:27], off offset:3776 sc1 nt
.LBB0_229:
	s_or_b64 exec, exec, s[38:39]
	v_mov_b32_e32 v62, 0
	v_mov_b32_e32 v63, 0
	s_and_saveexec_b64 s[38:39], s[2:3]
	s_cbranch_execz .LBB0_231
	v_lshl_add_u64 v[26:27], v[12:13], 0, v[4:5]
	v_add_co_u32_e32 v26, vcc, 0xee000, v26
	s_nop 1
	v_addc_co_u32_e32 v27, vcc, 0, v27, vcc
	global_load_dword v63, v[26:27], off offset:1792 sc1 nt
.LBB0_231:
	s_or_b64 exec, exec, s[38:39]
	s_and_saveexec_b64 s[38:39], s[2:3]
	s_cbranch_execz .LBB0_233
	v_lshl_add_u64 v[26:27], v[12:13], 0, v[4:5]
	v_add_co_u32_e32 v26, vcc, 0xf6000, v26
	s_nop 1
	v_addc_co_u32_e32 v27, vcc, 0, v27, vcc
	global_load_dword v62, v[26:27], off offset:3904 sc1 nt
.LBB0_233:
	s_or_b64 exec, exec, s[38:39]
	v_mov_b32_e32 v26, 0
	v_mov_b32_e32 v27, 0
	s_and_saveexec_b64 s[38:39], s[2:3]
	s_cbranch_execz .LBB0_235
	v_lshl_add_u64 v[64:65], v[12:13], 0, v[4:5]
	v_add_co_u32_e32 v64, vcc, 0xff000, v64
	s_nop 1
	v_addc_co_u32_e32 v65, vcc, 0, v65, vcc
	global_load_dword v27, v[64:65], off offset:1920 sc1 nt
.LBB0_235:
	s_or_b64 exec, exec, s[38:39]
	s_and_saveexec_b64 s[38:39], s[2:3]
	s_cbranch_execz .LBB0_237
	v_lshl_add_u64 v[12:13], v[12:13], 0, v[4:5]
	v_add_co_u32_e32 v12, vcc, 0x107000, v12
	s_nop 1
	v_addc_co_u32_e32 v13, vcc, 0, v13, vcc
	global_load_dword v26, v[12:13], off offset:4032 sc1 nt

; #define LAS __attribute__((address_space(3)))
; __device__ __forceinline__ void transpose_item(const float* colp, int N, const float* gk, bf16_t* WT, int ldw, int koff, int k0, int n0, LAS float* scr, int lane) {
;     float v[32];
; #pragma unroll
;     for (int i = 0; i < 32; ++i) { const int kk = 2 * i + (lane >> 5); v[i] = colp ? colp[(size_t)(k0 + kk) * N] : 0.f; }
; __device__ __forceinline__ void p0_prologue(const Args& a, LAS unsigned char* lds, int gw, int NGW, int wave, int lane) {
;     ...
;         r -= 2 * I_GU;
;         if (r < 2 * I_D) {
;             const bool second = r >= I_D; if (second) r -= I_D;
;             const int nblk = DM / 32, kb = r / nblk, nb = r % nblk, n = nb * 32 + (lane & 31);
;             transpose_item((second ? a.w2d : a.w1d) + n, DM, nullptr, (bf16_t*)(ws + (second ? WS_W2D : WS_W1D)), DFF, 0, kb * 64, nb * 32, scr, lane);
;             continue;
.LBB0_263:
	s_andn2_b64 vcc, exec, s[2:3]
	s_cbranch_vccnz .LBB0_329
	s_cmpk_gt_u32 s87, 0x1b7f
	s_cselect_b64 s[38:39], -1, 0
	s_and_b64 s[2:3], s[38:39], exec
	s_cselect_b32 s2, s83, 0xffffea00
	s_add_i32 s40, s2, s87
	s_lshl_b32 s2, s40, 5
	s_and_b32 s6, s2, 0x3e0
	v_readlane_b32 s48, v245, 1
	s_and_b64 s[2:3], s[38:39], exec
	v_readlane_b32 s52, v245, 5
	v_readlane_b32 s53, v245, 6
	s_cselect_b32 s3, s53, s19
	s_cselect_b32 s2, s52, s18
	s_lshl_b32 s40, s40, 1
	v_or_b32_e32 v4, s6, v3
	s_and_b32 s42, s40, 0x7fffffc0
	v_lshlrev_b32_e32 v4, 2, v4
	s_cmp_lg_u64 s[2:3], 0
	v_lshl_add_u64 v[10:11], s[2:3], 0, v[4:5]
	s_cselect_b64 s[40:41], -1, 0
	s_cmp_eq_u64 s[2:3], 0
	v_or_b32_e32 v4, s42, v0
	v_mov_b32_e32 v13, 0
	v_mov_b32_e32 v12, 0
	v_readlane_b32 s49, v245, 2
	v_readlane_b32 s50, v245, 3
	v_readlane_b32 s51, v245, 4
	v_readlane_b32 s54, v245, 7
	v_readlane_b32 s55, v245, 8
	s_cbranch_scc1 .LBB0_266
	v_lshlrev_b64 v[14:15], 12, v[4:5]
	v_lshl_add_u64 v[14:15], v[10:11], 0, v[14:15]
	global_load_dword v12, v[14:15], off sc1 nt

; #define LAS __attribute__((address_space(3)))
; __device__ __forceinline__ void transpose_item(const float* colp, int N, const float* gk, bf16_t* WT, int ldw, int koff, int k0, int n0, LAS float* scr, int lane) {
;     float v[32];
; #pragma unroll
;     for (int i = 0; i < 32; ++i) { const int kk = 2 * i + (lane >> 5); v[i] = colp ? colp[(size_t)(k0 + kk) * N] : 0.f; }
; __device__ __forceinline__ void p0_prologue(const Args& a, LAS unsigned char* lds, int gw, int NGW, int wave, int lane) {
;     ...
;         int r = it;
;         if (r < 2 * I_GU) {
;             const bool second = r >= I_GU; if (second) r -= I_GU;
;             const int nblk = NGU / 32, kb = r / nblk, nb = r % nblk, n = nb * 32 + (lane & 31);
;             const float* wg = second ? a.w2g : a.w1g; const float* wu = second ? a.w2u : a.w1u;
;             const float* colp = (((n >> 7) & 1) ? wu : wg) + 128 * (n >> 8) + (n & 127);
;             transpose_item(colp, DFF, second ? a.g2 : a.g1, (bf16_t*)(ws + (second ? WS_W2GU : WS_W1GU)), DM, 0, kb * 64, nb * 32, scr, lane);
.LBB0_330:
	s_andn2_b64 vcc, exec, s[2:3]
	s_cbranch_vccnz .LBB0_26
	s_add_i32 s6, s87, 0xfffff500
	s_cmpk_gt_i32 s87, 0xaff
	s_cselect_b64 s[38:39], -1, 0
	s_and_b64 s[2:3], s[38:39], exec
	s_cselect_b32 s2, s6, s87
	v_readlane_b32 s48, v245, 1
	s_mul_hi_i32 s3, s2, 0x2e8ba2e9
	v_readlane_b32 s49, v245, 2
	v_readlane_b32 s50, v245, 3
	v_readlane_b32 s51, v245, 4
	s_cselect_b32 s40, s48, s14
	s_cselect_b32 s41, s49, s15
	s_cselect_b32 s42, s50, s16
	s_cselect_b32 s43, s51, s17
	s_lshr_b32 s6, s3, 31
	s_ashr_i32 s3, s3, 5
	s_add_i32 s44, s3, s6
	s_mul_i32 s3, s44, 0xb0
	s_sub_i32 s45, s2, s3
	s_lshl_b32 s6, s45, 5
	s_bitcmp0_b32 s45, 2
	s_cselect_b32 s3, s41, s43
	s_cselect_b32 s2, s40, s42
	s_lshl_b32 s40, s45, 4
	s_and_b32 s40, s40, 0xffffff80
	s_ashr_i32 s41, s40, 31
	s_lshl_b64 s[40:41], s[40:41], 2
	s_add_u32 s40, s2, s40
	s_addc_u32 s41, s3, s41
	s_and_b32 s42, s6, 0x60
	v_or_b32_e32 v4, s42, v3
	v_lshlrev_b32_e32 v4, 2, v4
	v_lshl_add_u64 v[28:29], s[40:41], 0, v[4:5]
	s_lshl_b32 s40, s44, 6
	s_cmp_lg_u64 s[2:3], 0
	s_cselect_b64 s[42:43], -1, 0
	s_cmp_eq_u64 s[2:3], 0
	v_or_b32_e32 v26, s40, v0
	v_mov_b32_e32 v62, 0
	v_mov_b32_e32 v63, 0
	v_readlane_b32 s52, v245, 5
	v_readlane_b32 s53, v245, 6
	v_readlane_b32 s54, v245, 7
	v_readlane_b32 s55, v245, 8
	s_cbranch_scc1 .LBB0_333
	v_mad_i64_i32 v[10:11], s[2:3], v26, s85, v[28:29]
	global_load_dword v63, v[10:11], off sc1 nt
.LBB0_333:
	v_cndmask_b32_e64 v4, 0, 1, s[42:43]
	v_cmp_ne_u32_e64 s[2:3], 1, v4
	s_andn2_b64 vcc, exec, s[42:43]
	s_cbranch_vccnz .LBB0_335
	v_or_b32_e32 v4, 2, v26
	v_mad_i64_i32 v[10:11], s[42:43], v4, s85, v[28:29]
	global_load_dword v62, v[10:11], off sc1 nt
.LBB0_335:
	v_mov_b32_e32 v24, 0
	s_and_b64 vcc, exec, s[2:3]
	v_mov_b32_e32 v25, 0
	s_cbranch_vccnz .LBB0_337
	v_or_b32_e32 v4, 4, v26
	v_mad_i64_i32 v[10:11], s[42:43], v4, s85, v[28:29]
	global_load_dword v25, v[10:11], off sc1 nt
.LBB0_337:
	s_and_b64 vcc, exec, s[2:3]
	s_cbranch_vccnz .LBB0_339
	v_or_b32_e32 v4, 6, v26
	v_mad_i64_i32 v[10:11], s[42:43], v4, s85, v[28:29]
	global_load_dword v24, v[10:11], off sc1 nt
.LBB0_339:
	v_mov_b32_e32 v60, 0
	s_and_b64 vcc, exec, s[2:3]
	v_mov_b32_e32 v61, 0
	s_cbranch_vccnz .LBB0_341
	v_or_b32_e32 v4, 8, v26
	v_mad_i64_i32 v[10:11], s[42:43], v4, s85, v[28:29]
	global_load_dword v61, v[10:11], off sc1 nt
.LBB0_341:
	s_and_b64 vcc, exec, s[2:3]
	s_cbranch_vccnz .LBB0_343
	v_or_b32_e32 v4, 10, v26
	v_mad_i64_i32 v[10:11], s[42:43], v4, s85, v[28:29]
	global_load_dword v60, v[10:11], off sc1 nt
.LBB0_343:
	v_mov_b32_e32 v22, 0
	s_and_b64 vcc, exec, s[2:3]
	v_mov_b32_e32 v23, 0
	s_cbranch_vccnz .LBB0_345
	v_or_b32_e32 v4, 12, v26
	v_mad_i64_i32 v[10:11], s[42:43], v4, s85, v[28:29]
	global_load_dword v23, v[10:11], off sc1 nt
.LBB0_345:
	s_and_b64 vcc, exec, s[2:3]
	s_cbranch_vccnz .LBB0_347
	v_or_b32_e32 v4, 14, v26
	v_mad_i64_i32 v[10:11], s[42:43], v4, s85, v[28:29]
	global_load_dword v22, v[10:11], off sc1 nt
.LBB0_347:
	v_mov_b32_e32 v58, 0
	s_and_b64 vcc, exec, s[2:3]
	v_mov_b32_e32 v59, 0
	s_cbranch_vccnz .LBB0_349
	v_or_b32_e32 v4, 16, v26
	v_mad_i64_i32 v[10:11], s[42:43], v4, s85, v[28:29]
	global_load_dword v59, v[10:11], off sc1 nt
.LBB0_349:
	s_and_b64 vcc, exec, s[2:3]
	s_cbranch_vccnz .LBB0_351
	v_or_b32_e32 v4, 18, v26
	v_mad_i64_i32 v[10:11], s[42:43], v4, s85, v[28:29]
	global_load_dword v58, v[10:11], off sc1 nt
.LBB0_351:
	v_mov_b32_e32 v20, 0
	s_and_b64 vcc, exec, s[2:3]
	v_mov_b32_e32 v21, 0
	s_cbranch_vccnz .LBB0_353
	v_or_b32_e32 v4, 20, v26
	v_mad_i64_i32 v[10:11], s[42:43], v4, s85, v[28:29]
	global_load_dword v21, v[10:11], off sc1 nt
.LBB0_353:
	s_and_b64 vcc, exec, s[2:3]
	s_cbranch_vccnz .LBB0_355
	v_or_b32_e32 v4, 22, v26
	v_mad_i64_i32 v[10:11], s[42:43], v4, s85, v[28:29]
	global_load_dword v20, v[10:11], off sc1 nt
.LBB0_355:
	v_mov_b32_e32 v56, 0
	s_and_b64 vcc, exec, s[2:3]
	v_mov_b32_e32 v57, 0
	s_cbranch_vccnz .LBB0_357
	v_or_b32_e32 v4, 24, v26
	v_mad_i64_i32 v[10:11], s[42:43], v4, s85, v[28:29]
	global_load_dword v57, v[10:11], off sc1 nt
.LBB0_357:
	s_and_b64 vcc, exec, s[2:3]
	s_cbranch_vccnz .LBB0_359
	v_or_b32_e32 v4, 26, v26
	v_mad_i64_i32 v[10:11], s[42:43], v4, s85, v[28:29]
	global_load_dword v56, v[10:11], off sc1 nt
.LBB0_359:
	v_mov_b32_e32 v18, 0
	s_and_b64 vcc, exec, s[2:3]
	v_mov_b32_e32 v19, 0
	s_cbranch_vccnz .LBB0_361
	v_or_b32_e32 v4, 28, v26
	v_mad_i64_i32 v[10:11], s[42:43], v4, s85, v[28:29]
	global_load_dword v19, v[10:11], off sc1 nt
; #define LAS __attribute__((address_space(3)))
; __device__ __forceinline__ void transpose_item(const float* colp, int N, const float* gk, bf16_t* WT, int ldw, int koff, int k0, int n0, LAS float* scr, int lane) {
;     float v[32];
; #pragma unroll
;     for (int i = 0; i < 32; ++i) { const int kk = 2 * i + (lane >> 5); v[i] = colp ? colp[(size_t)(k0 + kk) * N] : 0.f; }
; #pragma unroll
;     for (int i = 0; i < 32; ++i) { const int kk = 2 * i + (lane >> 5); scr[kk * 33 + (lane & 31)] = gk ? v[i] * gk[k0 + kk] : v[i]; }
; __device__ __forceinline__ void p0_prologue(const Args& a, LAS unsigned char* lds, int gw, int NGW, int wave, int lane) {
;     ...
;         int r = it;
;         if (r < 2 * I_GU) {
;             const bool second = r >= I_GU; if (second) r -= I_GU;
;             const int nblk = NGU / 32, kb = r / nblk, nb = r % nblk, n = nb * 32 + (lane & 31);
;             const float* wg = second ? a.w2g : a.w1g; const float* wu = second ? a.w2u : a.w1u;
;             const float* colp = (((n >> 7) & 1) ? wu : wg) + 128 * (n >> 8) + (n & 127);
;             transpose_item(colp, DFF, second ? a.g2 : a.g1, (bf16_t*)(ws + (second ? WS_W2GU : WS_W1GU)), DM, 0, kb * 64, nb * 32, scr, lane);
.LBB0_361:
	s_and_b64 vcc, exec, s[2:3]
	s_cbranch_vccnz .LBB0_363
	v_or_b32_e32 v4, 30, v26
	v_mad_i64_i32 v[10:11], s[42:43], v4, s85, v[28:29]
	global_load_dword v18, v[10:11], off sc1 nt
.LBB0_363:
	v_mov_b32_e32 v54, 0
	s_and_b64 vcc, exec, s[2:3]
	v_mov_b32_e32 v55, 0
	s_cbranch_vccnz .LBB0_365
	v_or_b32_e32 v4, 32, v26
	v_mad_i64_i32 v[10:11], s[42:43], v4, s85, v[28:29]
	global_load_dword v55, v[10:11], off sc1 nt
.LBB0_365:
	s_and_b64 vcc, exec, s[2:3]
	s_cbranch_vccnz .LBB0_367
	v_or_b32_e32 v4, 34, v26
	v_mad_i64_i32 v[10:11], s[42:43], v4, s85, v[28:29]
	global_load_dword v54, v[10:11], off sc1 nt
.LBB0_367:
	v_mov_b32_e32 v16, 0
	s_and_b64 vcc, exec, s[2:3]
	v_mov_b32_e32 v17, 0
	s_cbranch_vccnz .LBB0_369
	v_or_b32_e32 v4, 36, v26
	v_mad_i64_i32 v[10:11], s[42:43], v4, s85, v[28:29]
	global_load_dword v17, v[10:11], off sc1 nt
.LBB0_369:
	s_and_b64 vcc, exec, s[2:3]
	s_cbranch_vccnz .LBB0_371
	v_or_b32_e32 v4, 38, v26
	v_mad_i64_i32 v[10:11], s[42:43], v4, s85, v[28:29]
	global_load_dword v16, v[10:11], off sc1 nt
.LBB0_371:
	v_mov_b32_e32 v52, 0
	s_and_b64 vcc, exec, s[2:3]
	v_mov_b32_e32 v53, 0
	s_cbranch_vccnz .LBB0_373
	v_or_b32_e32 v4, 40, v26
	v_mad_i64_i32 v[10:11], s[42:43], v4, s85, v[28:29]
	global_load_dword v53, v[10:11], off sc1 nt
.LBB0_373:
	s_and_b64 vcc, exec, s[2:3]
	s_cbranch_vccnz .LBB0_375
	v_or_b32_e32 v4, 42, v26
	v_mad_i64_i32 v[10:11], s[42:43], v4, s85, v[28:29]
	global_load_dword v52, v[10:11], off sc1 nt
.LBB0_375:
	v_mov_b32_e32 v14, 0
	s_and_b64 vcc, exec, s[2:3]
	v_mov_b32_e32 v15, 0
	s_cbranch_vccnz .LBB0_377
	v_or_b32_e32 v4, 44, v26
	v_mad_i64_i32 v[10:11], s[42:43], v4, s85, v[28:29]
	global_load_dword v15, v[10:11], off sc1 nt
.LBB0_377:
	s_and_b64 vcc, exec, s[2:3]
	s_cbranch_vccnz .LBB0_379
	v_or_b32_e32 v4, 46, v26
	v_mad_i64_i32 v[10:11], s[42:43], v4, s85, v[28:29]
	global_load_dword v14, v[10:11], off sc1 nt
.LBB0_379:
	v_mov_b32_e32 v50, 0
	s_and_b64 vcc, exec, s[2:3]
	v_mov_b32_e32 v51, 0
	s_cbranch_vccnz .LBB0_381
	v_or_b32_e32 v4, 48, v26
	v_mad_i64_i32 v[10:11], s[42:43], v4, s85, v[28:29]
	global_load_dword v51, v[10:11], off sc1 nt
.LBB0_381:
	s_and_b64 vcc, exec, s[2:3]
	s_cbranch_vccnz .LBB0_383
	v_or_b32_e32 v4, 50, v26
	v_mad_i64_i32 v[10:11], s[42:43], v4, s85, v[28:29]
	global_load_dword v50, v[10:11], off sc1 nt
.LBB0_383:
	v_mov_b32_e32 v12, 0
	s_and_b64 vcc, exec, s[2:3]
	v_mov_b32_e32 v13, 0
	s_cbranch_vccnz .LBB0_385
	v_or_b32_e32 v4, 52, v26
	v_mad_i64_i32 v[10:11], s[42:43], v4, s85, v[28:29]
	global_load_dword v13, v[10:11], off sc1 nt
.LBB0_385:
	s_and_b64 vcc, exec, s[2:3]
	s_cbranch_vccnz .LBB0_387
	v_or_b32_e32 v4, 54, v26
	v_mad_i64_i32 v[10:11], s[42:43], v4, s85, v[28:29]
	global_load_dword v12, v[10:11], off sc1 nt
.LBB0_387:
	v_mov_b32_e32 v4, 0
	s_and_b64 vcc, exec, s[2:3]
	v_mov_b32_e32 v49, 0
	s_cbranch_vccnz .LBB0_389
	v_or_b32_e32 v10, 56, v26
	v_mad_i64_i32 v[10:11], s[42:43], v10, s85, v[28:29]
	global_load_dword v49, v[10:11], off sc1 nt
.LBB0_389:
	s_and_b64 vcc, exec, s[2:3]
	s_cbranch_vccnz .LBB0_391
	v_or_b32_e32 v4, 58, v26
	v_mad_i64_i32 v[10:11], s[42:43], v4, s85, v[28:29]
	global_load_dword v4, v[10:11], off sc1 nt
.LBB0_391:
	v_mov_b32_e32 v10, 0
	s_and_b64 vcc, exec, s[2:3]
	v_mov_b32_e32 v11, 0
	s_cbranch_vccnz .LBB0_393
	v_or_b32_e32 v11, 60, v26
	v_mad_i64_i32 v[64:65], s[42:43], v11, s85, v[28:29]
	global_load_dword v11, v[64:65], off sc1 nt
.LBB0_393:
	s_and_b64 vcc, exec, s[2:3]
	s_cbranch_vccnz .LBB0_395
	v_or_b32_e32 v10, 62, v26
	v_mad_i64_i32 v[28:29], s[2:3], v10, s85, v[28:29]
	global_load_dword v10, v[28:29], off sc1 nt
.LBB0_395:
	s_and_b64 s[2:3], s[38:39], exec
	s_cselect_b32 s43, s71, s13
	s_cselect_b32 s42, s70, s12
	s_cmp_lg_u64 s[42:43], 0
	s_cselect_b64 s[44:45], -1, 0
	s_cmp_eq_u64 s[42:43], 0
	v_add_u32_e32 v28, v30, v37
	s_cbranch_scc1 .LBB0_418
	v_ashrrev_i32_e32 v27, 31, v26
	s_ashr_i32 s41, s40, 31
	v_lshl_add_u64 v[26:27], v[26:27], 2, s[42:43]
	v_lshl_add_u64 v[64:65], s[40:41], 0, v[0:1]
	v_lshl_add_u64 v[64:65], v[64:65], 2, s[42:43]
	global_load_dword v29, v[26:27], off sc1 nt
	global_load_dword v66, v[64:65], off offset:8 sc1 nt
	s_nop 0
	global_load_dword v27, v[64:65], off offset:16 sc1 nt
	global_load_dword v26, v[64:65], off offset:24 sc1 nt
	s_waitcnt vmcnt(3)
	v_mul_f32_e32 v29, v63, v29
	s_waitcnt vmcnt(2)
	v_mul_f32_e32 v64, v62, v66
	ds_write_b32 v31, v29
	s_waitcnt vmcnt(0)
	v_pk_mul_f32 v[26:27], v[24:25], v[26:27]
	ds_write_b32 v28, v64
	s_cbranch_execnz .LBB0_398

; __device__ __forceinline__ void transpose_item(const float* colp, int N, const float* gk, bf16_t* WT, int ldw, int koff, int k0, int n0, LAS float* scr, int lane) {
;     ...
;     for (int i = 0; i < 32; ++i) { const int kk = 2 * i + (lane >> 5); v[i] = colp ? colp[(size_t)(k0 + kk) * N] : 0.f; }
; #pragma unroll
;     for (int i = 0; i < 32; ++i) { const int kk = 2 * i + (lane >> 5); scr[kk * 33 + (lane & 31)] = gk ? v[i] * gk[k0 + kk] : v[i]; }
.LBB0_398:
	s_waitcnt vmcnt(0)
	v_add_u32_e32 v24, v30, v38
	ds_write2_b32 v24, v27, v26 offset1:66
	v_cndmask_b32_e64 v24, 0, 1, s[44:45]
	v_cmp_ne_u32_e64 s[2:3], 1, v24
	s_andn2_b64 vcc, exec, s[44:45]
	v_add_u32_e32 v26, v30, v39
	s_cbranch_vccnz .LBB0_419
	s_ashr_i32 s41, s40, 31
	v_lshl_add_u64 v[24:25], s[40:41], 0, v[0:1]
	v_lshl_add_u64 v[24:25], v[24:25], 2, s[42:43]
	global_load_dword v27, v[24:25], off offset:32 sc1 nt
	global_load_dword v62, v[24:25], off offset:40 sc1 nt
	global_load_dword v29, v[24:25], off offset:48 sc1 nt
	global_load_dword v28, v[24:25], off offset:56 sc1 nt
	s_waitcnt vmcnt(3)
	v_mul_f32_e32 v27, v61, v27
	s_waitcnt vmcnt(2)
	v_mul_f32_e32 v62, v60, v62
	ds_write2_b32 v26, v27, v62 offset1:66
	s_waitcnt vmcnt(0)
	v_pk_mul_f32 v[24:25], v[22:23], v[28:29]
	s_cbranch_execnz .LBB0_401

; __device__ __forceinline__ void transpose_item(const float* colp, int N, const float* gk, bf16_t* WT, int ldw, int koff, int k0, int n0, LAS float* scr, int lane) {
;     ...
;     for (int i = 0; i < 32; ++i) { const int kk = 2 * i + (lane >> 5); v[i] = colp ? colp[(size_t)(k0 + kk) * N] : 0.f; }
; #pragma unroll
;     for (int i = 0; i < 32; ++i) { const int kk = 2 * i + (lane >> 5); scr[kk * 33 + (lane & 31)] = gk ? v[i] * gk[k0 + kk] : v[i]; }
.LBB0_401:
	v_add_u32_e32 v22, v30, v40
	ds_write2_b32 v22, v25, v24 offset1:66
	s_and_b64 vcc, exec, s[2:3]
	v_add_u32_e32 v24, v30, v41
	s_cbranch_vccnz .LBB0_420
	s_ashr_i32 s41, s40, 31
	v_lshl_add_u64 v[22:23], s[40:41], 0, v[0:1]
	v_lshl_add_u64 v[22:23], v[22:23], 2, s[42:43]
	global_load_dword v25, v[22:23], off offset:64 sc1 nt
	global_load_dword v28, v[22:23], off offset:72 sc1 nt
	global_load_dword v27, v[22:23], off offset:80 sc1 nt
	global_load_dword v26, v[22:23], off offset:88 sc1 nt
	s_waitcnt vmcnt(3)
	v_mul_f32_e32 v25, v59, v25
	s_waitcnt vmcnt(2)
	v_mul_f32_e32 v28, v58, v28
	ds_write2_b32 v24, v25, v28 offset1:66
	s_waitcnt vmcnt(0)
	v_pk_mul_f32 v[22:23], v[20:21], v[26:27]
	s_cbranch_execnz .LBB0_404

; __device__ __forceinline__ void transpose_item(const float* colp, int N, const float* gk, bf16_t* WT, int ldw, int koff, int k0, int n0, LAS float* scr, int lane) {
;     ...
;     for (int i = 0; i < 32; ++i) { const int kk = 2 * i + (lane >> 5); v[i] = colp ? colp[(size_t)(k0 + kk) * N] : 0.f; }
; #pragma unroll
;     for (int i = 0; i < 32; ++i) { const int kk = 2 * i + (lane >> 5); scr[kk * 33 + (lane & 31)] = gk ? v[i] * gk[k0 + kk] : v[i]; }
.LBB0_404:
	v_add_u32_e32 v20, v30, v42
	ds_write2_b32 v20, v23, v22 offset1:66
	s_and_b64 vcc, exec, s[2:3]
	v_add_u32_e32 v22, v30, v43
	s_cbranch_vccnz .LBB0_421
	s_ashr_i32 s41, s40, 31
	v_lshl_add_u64 v[20:21], s[40:41], 0, v[0:1]
	v_lshl_add_u64 v[20:21], v[20:21], 2, s[42:43]
	global_load_dword v23, v[20:21], off offset:96 sc1 nt
	global_load_dword v26, v[20:21], off offset:104 sc1 nt
	global_load_dword v25, v[20:21], off offset:112 sc1 nt
	global_load_dword v24, v[20:21], off offset:120 sc1 nt
	s_waitcnt vmcnt(3)
	v_mul_f32_e32 v23, v57, v23
	s_waitcnt vmcnt(2)
	v_mul_f32_e32 v26, v56, v26
	ds_write2_b32 v22, v23, v26 offset1:66
	s_waitcnt vmcnt(0)
	v_pk_mul_f32 v[20:21], v[18:19], v[24:25]
	s_cbranch_execnz .LBB0_407

; __device__ __forceinline__ void transpose_item(const float* colp, int N, const float* gk, bf16_t* WT, int ldw, int koff, int k0, int n0, LAS float* scr, int lane) {
;     ...
;     for (int i = 0; i < 32; ++i) { const int kk = 2 * i + (lane >> 5); v[i] = colp ? colp[(size_t)(k0 + kk) * N] : 0.f; }
; #pragma unroll
;     for (int i = 0; i < 32; ++i) { const int kk = 2 * i + (lane >> 5); scr[kk * 33 + (lane & 31)] = gk ? v[i] * gk[k0 + kk] : v[i]; }
.LBB0_407:
	v_add_u32_e32 v18, v30, v44
	ds_write2_b32 v18, v21, v20 offset1:66
	s_and_b64 vcc, exec, s[2:3]
	v_add_u32_e32 v20, v30, v45
	s_cbranch_vccnz .LBB0_422
	s_ashr_i32 s41, s40, 31
	v_lshl_add_u64 v[18:19], s[40:41], 0, v[0:1]
	v_lshl_add_u64 v[18:19], v[18:19], 2, s[42:43]
	global_load_dword v21, v[18:19], off offset:128 sc1 nt
	global_load_dword v24, v[18:19], off offset:136 sc1 nt
	global_load_dword v23, v[18:19], off offset:144 sc1 nt
	global_load_dword v22, v[18:19], off offset:152 sc1 nt
	s_waitcnt vmcnt(3)
	v_mul_f32_e32 v21, v55, v21
	s_waitcnt vmcnt(2)
	v_mul_f32_e32 v24, v54, v24
	ds_write2_b32 v20, v21, v24 offset1:66
	s_waitcnt vmcnt(0)
	v_pk_mul_f32 v[18:19], v[16:17], v[22:23]
	s_cbranch_execnz .LBB0_410

; __device__ __forceinline__ void transpose_item(const float* colp, int N, const float* gk, bf16_t* WT, int ldw, int koff, int k0, int n0, LAS float* scr, int lane) {
;     ...
;     for (int i = 0; i < 32; ++i) { const int kk = 2 * i + (lane >> 5); v[i] = colp ? colp[(size_t)(k0 + kk) * N] : 0.f; }
; #pragma unroll
;     for (int i = 0; i < 32; ++i) { const int kk = 2 * i + (lane >> 5); scr[kk * 33 + (lane & 31)] = gk ? v[i] * gk[k0 + kk] : v[i]; }
.LBB0_410:
	v_add_u32_e32 v16, v30, v46
	ds_write2_b32 v16, v19, v18 offset1:66
	s_and_b64 vcc, exec, s[2:3]
	v_add_u32_e32 v18, v30, v47
	s_cbranch_vccnz .LBB0_423
	s_ashr_i32 s41, s40, 31
	v_lshl_add_u64 v[16:17], s[40:41], 0, v[0:1]
	v_lshl_add_u64 v[16:17], v[16:17], 2, s[42:43]
	global_load_dword v19, v[16:17], off offset:160 sc1 nt
	global_load_dword v22, v[16:17], off offset:168 sc1 nt
	global_load_dword v21, v[16:17], off offset:176 sc1 nt
	global_load_dword v20, v[16:17], off offset:184 sc1 nt
	s_waitcnt vmcnt(3)
	v_mul_f32_e32 v19, v53, v19
	s_waitcnt vmcnt(2)
	v_mul_f32_e32 v22, v52, v22
	ds_write2_b32 v18, v19, v22 offset1:66
	s_waitcnt vmcnt(0)
	v_pk_mul_f32 v[16:17], v[14:15], v[20:21]
	s_cbranch_execnz .LBB0_413

; __device__ __forceinline__ void transpose_item(const float* colp, int N, const float* gk, bf16_t* WT, int ldw, int koff, int k0, int n0, LAS float* scr, int lane) {
;     ...
;     for (int i = 0; i < 32; ++i) { const int kk = 2 * i + (lane >> 5); v[i] = colp ? colp[(size_t)(k0 + kk) * N] : 0.f; }
; #pragma unroll
;     for (int i = 0; i < 32; ++i) { const int kk = 2 * i + (lane >> 5); scr[kk * 33 + (lane & 31)] = gk ? v[i] * gk[k0 + kk] : v[i]; }
.LBB0_413:
	ds_write2_b32 v18, v17, v16 offset0:132 offset1:198
	s_and_b64 vcc, exec, s[2:3]
	v_add_u32_e32 v16, 0x400, v18
	s_cbranch_vccnz .LBB0_424
	s_ashr_i32 s41, s40, 31
	v_lshl_add_u64 v[14:15], s[40:41], 0, v[0:1]
	v_lshl_add_u64 v[14:15], v[14:15], 2, s[42:43]
	global_load_dword v17, v[14:15], off offset:192 sc1 nt
	global_load_dword v19, v[14:15], off offset:200 sc1 nt
	global_load_dword v21, v[14:15], off offset:208 sc1 nt
	global_load_dword v20, v[14:15], off offset:216 sc1 nt
	s_waitcnt vmcnt(3)
	v_mul_f32_e32 v17, v51, v17
	s_waitcnt vmcnt(2)
	v_mul_f32_e32 v19, v50, v19
	ds_write2_b32 v16, v17, v19 offset0:8 offset1:74
	s_waitcnt vmcnt(0)
	v_pk_mul_f32 v[14:15], v[12:13], v[20:21]
	s_cbranch_execnz .LBB0_416

; __device__ __forceinline__ void transpose_item(const float* colp, int N, const float* gk, bf16_t* WT, int ldw, int koff, int k0, int n0, LAS float* scr, int lane) {
;     ...
;     for (int i = 0; i < 32; ++i) { const int kk = 2 * i + (lane >> 5); v[i] = colp ? colp[(size_t)(k0 + kk) * N] : 0.f; }
; #pragma unroll
;     for (int i = 0; i < 32; ++i) { const int kk = 2 * i + (lane >> 5); scr[kk * 33 + (lane & 31)] = gk ? v[i] * gk[k0 + kk] : v[i]; }
.LBB0_416:
	ds_write2_b32 v16, v15, v14 offset0:140 offset1:206
	s_and_b64 vcc, exec, s[2:3]
	v_add_u32_e32 v14, 0x800, v18
	s_cbranch_vccnz .LBB0_425
	s_ashr_i32 s41, s40, 31
	v_lshl_add_u64 v[12:13], s[40:41], 0, v[0:1]
	v_lshl_add_u64 v[12:13], v[12:13], 2, s[42:43]
	global_load_dword v15, v[12:13], off offset:224 sc1 nt
	global_load_dword v18, v[12:13], off offset:232 sc1 nt
	global_load_dword v17, v[12:13], off offset:240 sc1 nt
	global_load_dword v16, v[12:13], off offset:248 sc1 nt
	s_waitcnt vmcnt(3)
	v_mul_f32_e32 v15, v49, v15
	s_waitcnt vmcnt(2)
	v_mul_f32_e32 v18, v4, v18
	ds_write2_b32 v14, v15, v18 offset0:16 offset1:82
	s_waitcnt vmcnt(0)
	v_pk_mul_f32 v[12:13], v[10:11], v[16:17]
	s_cbranch_execnz .LBB0_25
	s_branch .LBB0_426

; __device__ __forceinline__ void p0_prologue(const Args& a, LAS unsigned char* lds, int gw, int NGW, int wave, int lane) {
;     ...
;     for (int m0 = gw; m0 < M; m0 += 8 * NGW) {
;         f32x4 v[8][4];
; #pragma unroll
;         for (int r = 0; r < 8; ++r) { const int m = m0 + r * NGW; const f32x4* xr = (const f32x4*)(a.x + (size_t)(m < M ? m : gw) * DM) + lane;
; #pragma unroll
;             for (int j = 0; j < 4; ++j) v[r][j] = xr[64 * j]; }
; #pragma unroll
;         for (int r = 0; r < 8; ++r) { const int m = m0 + r * NGW; if (m >= M) break;
;             float s = 0.f;
; #pragma unroll
;             for (int j = 0; j < 4; ++j) s += (v[r][j].x * v[r][j].x + v[r][j].y * v[r][j].y) + (v[r][j].z * v[r][j].z + v[r][j].w * v[r][j].w);
;             s = wave_sum(s);
;             if (lane == 0) ss0[m] = s;
.LBB0_440:
	s_add_i32 s5, s46, s47
	s_cmp_lt_i32 s5, 0x8000
	s_cselect_b64 s[36:37], -1, 0
	s_and_b64 s[16:17], s[36:37], exec
	s_cselect_b32 s16, s5, s4
	s_ashr_i32 s17, s16, 31
	s_add_i32 s5, s0, s5
	s_lshl_b64 s[16:17], s[16:17], 12
	global_load_dwordx4 v[124:127], v[138:139], off offset:-3072 sc1 nt
	global_load_dwordx4 v[120:123], v[138:139], off offset:-2048 sc1 nt
	global_load_dwordx4 v[116:119], v[138:139], off offset:-1024 sc1 nt
	global_load_dwordx4 v[112:115], v[138:139], off sc1 nt
	s_cmp_lt_i32 s5, 0x8000
	s_cselect_b64 s[34:35], -1, 0
	s_waitcnt vmcnt(8)
	v_lshl_add_u64 v[0:1], v[132:133], 0, s[16:17]
	s_and_b64 s[16:17], s[34:35], exec
	s_cselect_b32 s16, s5, s4
	s_ashr_i32 s17, s16, 31
	s_add_i32 s5, s0, s5
	s_lshl_b64 s[16:17], s[16:17], 12
	s_cmp_lt_i32 s5, 0x8000
	s_cselect_b64 s[30:31], -1, 0
	global_load_dwordx4 v[108:111], v[0:1], off sc1 nt
	global_load_dwordx4 v[104:107], v[0:1], off offset:1024 sc1 nt
	global_load_dwordx4 v[100:103], v[0:1], off offset:2048 sc1 nt
	global_load_dwordx4 v[96:99], v[0:1], off offset:3072 sc1 nt
	v_lshl_add_u64 v[0:1], v[132:133], 0, s[16:17]
	s_and_b64 s[16:17], s[30:31], exec
	s_cselect_b32 s16, s5, s4
	s_ashr_i32 s17, s16, 31
	s_add_i32 s5, s0, s5
	s_lshl_b64 s[16:17], s[16:17], 12
	s_cmp_lt_i32 s5, 0x8000
	s_cselect_b64 s[22:23], -1, 0
	global_load_dwordx4 v[92:95], v[0:1], off sc1 nt
	global_load_dwordx4 v[88:91], v[0:1], off offset:1024 sc1 nt
	global_load_dwordx4 v[80:83], v[0:1], off offset:2048 sc1 nt
	global_load_dwordx4 v[72:75], v[0:1], off offset:3072 sc1 nt
	v_lshl_add_u64 v[0:1], v[132:133], 0, s[16:17]
	s_and_b64 s[16:17], s[22:23], exec
	s_cselect_b32 s16, s5, s4
	s_ashr_i32 s17, s16, 31
	s_add_i32 s5, s0, s5
	s_lshl_b64 s[38:39], s[16:17], 12
	s_cmp_lt_i32 s5, 0x8000
	s_cselect_b64 s[20:21], -1, 0
	s_and_b64 s[16:17], s[20:21], exec
	s_cselect_b32 s16, s5, s4
	s_ashr_i32 s17, s16, 31
	s_add_i32 s5, s0, s5
	s_lshl_b64 s[50:51], s[16:17], 12
	s_cmp_lt_i32 s5, 0x8000
	s_cselect_b64 s[18:19], -1, 0
	s_and_b64 s[16:17], s[18:19], exec
	s_cselect_b32 s16, s5, s4
	s_ashr_i32 s17, s16, 31
	s_add_i32 s5, s0, s5
	s_lshl_b64 s[52:53], s[16:17], 12
	s_cmp_lt_i32 s5, 0x8000
	s_cselect_b64 s[16:17], -1, 0
	s_and_b64 s[64:65], s[16:17], exec
	s_cselect_b32 s64, s5, s4
	global_load_dwordx4 v[84:87], v[0:1], off sc1 nt
	global_load_dwordx4 v[76:79], v[0:1], off offset:1024 sc1 nt
	global_load_dwordx4 v[68:71], v[0:1], off offset:2048 sc1 nt
	global_load_dwordx4 v[64:67], v[0:1], off offset:3072 sc1 nt
	v_lshl_add_u64 v[0:1], v[132:133], 0, s[38:39]
	s_ashr_i32 s65, s64, 31
	global_load_dwordx4 v[60:63], v[0:1], off sc1 nt
	global_load_dwordx4 v[56:59], v[0:1], off offset:1024 sc1 nt
	global_load_dwordx4 v[52:55], v[0:1], off offset:2048 sc1 nt
	global_load_dwordx4 v[48:51], v[0:1], off offset:3072 sc1 nt
	v_lshl_add_u64 v[0:1], v[132:133], 0, s[50:51]
	s_lshl_b64 s[64:65], s[64:65], 12
	global_load_dwordx4 v[44:47], v[0:1], off sc1 nt
	global_load_dwordx4 v[40:43], v[0:1], off offset:1024 sc1 nt
	global_load_dwordx4 v[36:39], v[0:1], off offset:2048 sc1 nt
	global_load_dwordx4 v[32:35], v[0:1], off offset:3072 sc1 nt
	v_lshl_add_u64 v[0:1], v[132:133], 0, s[52:53]
	global_load_dwordx4 v[28:31], v[0:1], off sc1 nt
	global_load_dwordx4 v[24:27], v[0:1], off offset:1024 sc1 nt
	global_load_dwordx4 v[20:23], v[0:1], off offset:2048 sc1 nt
	global_load_dwordx4 v[16:19], v[0:1], off offset:3072 sc1 nt
	v_lshl_add_u64 v[0:1], v[132:133], 0, s[64:65]
	global_load_dwordx4 v[12:15], v[0:1], off sc1 nt
	global_load_dwordx4 v[8:11], v[0:1], off offset:1024 sc1 nt
	global_load_dwordx4 v[4:7], v[0:1], off offset:2048 sc1 nt
	s_nop 0
	global_load_dwordx4 v[0:3], v[0:1], off offset:3072 sc1 nt
	s_waitcnt vmcnt(31)
	v_mul_f32_e32 v128, v125, v125
	v_mul_f32_e32 v146, v127, v127
	s_waitcnt vmcnt(30)
	v_mul_f32_e32 v147, v121, v121
	v_mul_f32_e32 v148, v123, v123
	s_waitcnt vmcnt(29)
	v_mul_f32_e32 v149, v117, v117
	v_mul_f32_e32 v150, v119, v119
	v_fmac_f32_e32 v128, v124, v124
	v_fmac_f32_e32 v146, v126, v126
	v_fmac_f32_e32 v147, v120, v120
	v_fmac_f32_e32 v148, v122, v122
	s_waitcnt vmcnt(28)
	v_mul_f32_e32 v151, v113, v113
	v_mul_f32_e32 v154, v115, v115
	v_fmac_f32_e32 v149, v116, v116
	v_fmac_f32_e32 v150, v118, v118
	v_add_f32_e32 v128, v128, v146
	v_add_f32_e32 v146, v147, v148
	v_fmac_f32_e32 v151, v112, v112
	v_fmac_f32_e32 v154, v114, v114
	v_add_f32_e32 v147, v149, v150
	v_add_f32_e32 v128, v146, v128
	v_add_f32_e32 v148, v151, v154
	v_add_f32_e32 v128, v147, v128
	v_add_f32_e32 v128, v148, v128
	ds_bpermute_b32 v146, v140, v128
	s_waitcnt lgkmcnt(0)
	v_add_f32_e32 v128, v128, v146
	ds_bpermute_b32 v146, v141, v128
	s_waitcnt lgkmcnt(0)
	v_add_f32_e32 v128, v128, v146
	ds_bpermute_b32 v146, v142, v128
	s_waitcnt lgkmcnt(0)
	v_add_f32_e32 v128, v128, v146
	ds_bpermute_b32 v146, v143, v128
	s_waitcnt lgkmcnt(0)
	v_add_f32_e32 v128, v128, v146
	ds_bpermute_b32 v146, v144, v128
	s_waitcnt lgkmcnt(0)
	v_add_f32_e32 v128, v128, v146
	ds_bpermute_b32 v146, v145, v128
	s_and_saveexec_b64 s[38:39], s[2:3]
	s_cbranch_execz .LBB0_442
	s_add_u32 s50, s74, s48
	s_waitcnt lgkmcnt(0)
	v_add_f32_e32 v128, v128, v146
	s_addc_u32 s51, s75, s49
	global_store_dword v129, v128, s[50:51]

; __device__ __forceinline__ void p0_prologue(const Args& a, LAS unsigned char* lds, int gw, int NGW, int wave, int lane) {
;     ...
;     float* rope = (float*)(ws + WS_ROPE);
;     for (int idx = gw * 64 + lane; idx < M * 8; idx += NGW * 64) {
;         const int row = idx >> 3, i = idx & 7;
;         const float inv = i == 0 ? 1.0f : i == 1 ? 0.1939227432012558f : i == 2 ? 0.03760603070259094f : i == 3 ? 0.007292664609849453f : i == 4 ? 0.0014142135623842478f
;                         : i == 5 ? 0.00027424818836152554f : i == 6 ? 5.3182957344688475e-05f : 1.0313385246263351e-05f;
;         const float ang = (float)a.pos[row] * inv; float sn, cs; sincosf(ang, &sn, &cs);
;         rope[(size_t)row * 16 + i] = cs; rope[(size_t)row * 16 + 8 + i] = sn;
;     }
.LBB0_484:
	s_or_b64 exec, exec, s[2:3]
	v_ashrrev_i32_e32 v4, 3, v6
	v_ashrrev_i32_e32 v5, 31, v4
	v_lshl_add_u64 v[14:15], v[4:5], 2, s[10:11]
	global_load_dword v14, v[14:15], off sc1 nt
	s_waitcnt vmcnt(0)
	v_cvt_f32_i32_e32 v14, v14
	v_mul_f32_e32 v14, v0, v14
	v_and_b32_e32 v15, 0x7fffffff, v14
	v_cmp_nlt_f32_e64 s[2:3], |v14|, s1
	s_and_saveexec_b64 s[4:5], s[2:3]
	s_xor_b64 s[14:15], exec, s[4:5]
	s_cbranch_execz .LBB0_486
	v_lshrrev_b32_e32 v0, 23, v15
	v_add_u32_e32 v0, 0xffffff88, v0
	v_cmp_lt_u32_e32 vcc, 63, v0
	s_nop 1
	v_cndmask_b32_e32 v16, 0, v11, vcc
	v_add_u32_e32 v0, v16, v0
	v_cmp_lt_u32_e64 s[2:3], 31, v0
	s_nop 1
	v_cndmask_b32_e64 v16, 0, v12, s[2:3]
	v_add_u32_e32 v0, v16, v0
	v_cmp_lt_u32_e64 s[4:5], 31, v0
	s_nop 1
	v_cndmask_b32_e64 v16, 0, v12, s[4:5]
	v_add_u32_e32 v30, v16, v0
	v_and_b32_e32 v0, 0x7fffff, v15
	v_or_b32_e32 v28, 0x800000, v0
	v_mad_u64_u32 v[16:17], s[6:7], v28, s16, 0
	v_mov_b32_e32 v0, v17
	v_mad_u64_u32 v[18:19], s[6:7], v28, s17, v[0:1]
	v_mov_b32_e32 v0, v19
	v_mad_u64_u32 v[20:21], s[6:7], v28, s18, v[0:1]
	v_mov_b32_e32 v0, v21
	v_mad_u64_u32 v[22:23], s[6:7], v28, s19, v[0:1]
	v_mov_b32_e32 v0, v23
	v_mad_u64_u32 v[24:25], s[6:7], v28, s20, v[0:1]
	v_mov_b32_e32 v0, v25
	v_mad_u64_u32 v[26:27], s[6:7], v28, s21, v[0:1]
	v_mov_b32_e32 v0, v27
	v_mad_u64_u32 v[28:29], s[6:7], v28, s22, v[0:1]
	v_cndmask_b32_e32 v17, v26, v22, vcc
	v_cndmask_b32_e32 v0, v28, v24, vcc
	v_cndmask_b32_e32 v21, v29, v26, vcc
	v_cndmask_b32_e64 v19, v0, v17, s[2:3]
	v_cndmask_b32_e64 v0, v21, v0, s[2:3]
	v_cndmask_b32_e32 v21, v24, v20, vcc
	v_cndmask_b32_e64 v17, v17, v21, s[2:3]
	v_cndmask_b32_e64 v0, v0, v19, s[4:5]
	v_cndmask_b32_e64 v19, v19, v17, s[4:5]
	v_sub_u32_e32 v23, 32, v30
	v_alignbit_b32 v24, v0, v19, v23
	v_cmp_eq_u32_e64 s[6:7], 0, v30
	v_cndmask_b32_e32 v16, v20, v16, vcc
	s_nop 0
	v_cndmask_b32_e64 v24, v24, v0, s[6:7]
	v_cndmask_b32_e32 v0, v22, v18, vcc
	v_cndmask_b32_e64 v18, v21, v0, s[2:3]
	v_cndmask_b32_e64 v17, v17, v18, s[4:5]
	v_alignbit_b32 v21, v19, v17, v23
	v_cndmask_b32_e64 v19, v21, v19, s[6:7]
	v_bfe_u32 v25, v24, 29, 1
	v_cndmask_b32_e64 v0, v0, v16, s[2:3]
	v_alignbit_b32 v21, v24, v19, 30
	v_sub_u32_e32 v26, 0, v25
	v_cndmask_b32_e64 v0, v18, v0, s[4:5]
	v_xor_b32_e32 v21, v21, v26
	v_alignbit_b32 v16, v17, v0, v23
	v_cndmask_b32_e64 v16, v16, v17, s[6:7]
	v_ffbh_u32_e32 v18, v21
	v_alignbit_b32 v17, v19, v16, 30
	v_min_u32_e32 v18, 32, v18
	v_alignbit_b32 v0, v16, v0, 30
	v_xor_b32_e32 v17, v17, v26
	v_sub_u32_e32 v19, 31, v18
	v_xor_b32_e32 v0, v0, v26
	v_alignbit_b32 v20, v21, v17, v19
	v_alignbit_b32 v0, v17, v0, v19
	v_alignbit_b32 v16, v20, v0, 9
	v_ffbh_u32_e32 v17, v16
	v_min_u32_e32 v17, 32, v17
	v_lshrrev_b32_e32 v22, 29, v24
	v_not_b32_e32 v19, v17
	v_alignbit_b32 v0, v16, v0, v19
	v_lshlrev_b32_e32 v16, 31, v22
	v_or_b32_e32 v19, 0x33000000, v16
	v_add_lshl_u32 v17, v17, v18, 23
	v_lshrrev_b32_e32 v0, 9, v0
	v_sub_u32_e32 v17, v19, v17
	v_or_b32_e32 v16, 0.5, v16
	v_lshlrev_b32_e32 v18, 23, v18
	v_or_b32_e32 v0, v17, v0
	v_lshrrev_b32_e32 v17, 9, v20
	v_sub_u32_e32 v16, v16, v18
	v_or_b32_e32 v16, v17, v16
	v_mul_f32_e32 v17, 0x3fc90fda, v16
	v_fma_f32 v18, v16, s23, -v17
	v_fmac_f32_e32 v18, 0x33a22168, v16
	v_fmac_f32_e32 v18, 0x3fc90fda, v0
	v_lshrrev_b32_e32 v16, 30, v24
	v_add_f32_e32 v0, v17, v18
	v_add_u32_e32 v16, v25, v16
